# dense attention: row-max chain moved back to the softmax segment so the MFMA segment carries only MFMA + LDS traffic
# baseline (speedup 1.0000x reference)
; #define SBAR() __builtin_amdgcn_sched_barrier(0)
; __device__ __forceinline__ void qkt(f32x16& p0, f32x16& p1, const bf16_t* Ks, const bf16x8* qr, int r32, int hi) {
;   p0 = f32x16{}; p1 = f32x16{};
; #pragma unroll
;   for (int d0 = 0; d0 < 8; ++d0) { int cb = (d0 * 16 + hi * 8) * 2;
;     bf16x8 b0 = *reinterpret_cast<const bf16x8*>((const char*)Ks + KSWZ(r32, cb));
;     bf16x8 b1 = *reinterpret_cast<const bf16x8*>((const char*)Ks + KSWZ(32 + r32, cb));
;     p0 = __builtin_amdgcn_mfma_f32_32x32x16_bf16(b0, qr[d0], p0, 0, 0, 0);
;     p1 = __builtin_amdgcn_mfma_f32_32x32x16_bf16(b1, qr[d0], p1, 0, 0, 0); }
; }
; __device__ __forceinline__ int v_st(int k, int c) { const int kk = (k & ~0xC) | ((k & 4) << 1) | ((k & 8) >> 1); return ((kk >> 3) * 4 + (c >> 5)) * 512 + ((kk & 7) * 32 + (c & 31)) * 2; }
; __device__ __forceinline__ int v_rd_base(int lane) { return ((lane & 3) << 3) | (((lane >> 2) & 3) << 6) | (((lane >> 4) & 1) << 5) | (((lane >> 5) & 1) << 8); }
; template <int OFF> __device__ __forceinline__ s16x4 tr_read(int vb) {
;   s16x4 r; asm volatile("ds_read_b64_tr_b16 %0, %1 offset:%2" : "=&v"(r) : "v"(vb), "i"(OFF) : "memory"); return r;
; }
; template <int D0> __device__ __forceinline__ void pv_one(f32x16& od, int vb, bf16x8 pa0, bf16x8 pa1, bf16x8 pa2, bf16x8 pa3) {
;   const s16x4 l0 = tr_read<v_rd_off(D0, 0, 0)>(vb), h0 = tr_read<v_rd_off(D0, 0, 1)>(vb), l1 = tr_read<v_rd_off(D0, 1, 0)>(vb), h1 = tr_read<v_rd_off(D0, 1, 1)>(vb);
;   const s16x4 l2 = tr_read<v_rd_off(D0, 2, 0)>(vb), h2 = tr_read<v_rd_off(D0, 2, 1)>(vb), l3 = tr_read<v_rd_off(D0, 3, 0)>(vb), h3 = tr_read<v_rd_off(D0, 3, 1)>(vb);
;   asm volatile("s_waitcnt lgkmcnt(0)" ::: "memory"); SBAR();
;     ...
;   od = __builtin_amdgcn_mfma_f32_32x32x16_bf16(pa0, PK(l0, h0), od, 0, 0, 0);
;   od = __builtin_amdgcn_mfma_f32_32x32x16_bf16(pa1, PK(l1, h1), od, 0, 0, 0);
;   od = __builtin_amdgcn_mfma_f32_32x32x16_bf16(pa2, PK(l2, h2), od, 0, 0, 0);
;   od = __builtin_amdgcn_mfma_f32_32x32x16_bf16(pa3, PK(l3, h3), od, 0, 0, 0);
;     ...
; }
; __device__ __forceinline__ void pv_d0(f32x16* o, int vb, bf16x8 pa0, bf16x8 pa1, bf16x8 pa2, bf16x8 pa3) {
;   pv_one<0>(o[0], vb, pa0, pa1, pa2, pa3); pv_one<1>(o[1], vb, pa0, pa1, pa2, pa3); pv_one<2>(o[2], vb, pa0, pa1, pa2, pa3); pv_one<3>(o[3], vb, pa0, pa1, pa2, pa3);
.Lda_lead:
	s_setprio 3
	s_waitcnt vmcnt(4)
	ds_write_b128 v197, v[134:137] offset:32768
	ds_write_b128 v197, v[138:141] offset:40960
	ds_write_b128 v185, v[142:145] offset:32768
	ds_write_b128 v185, v[146:149] offset:40960
	s_waitcnt lgkmcnt(10)
	v_mfma_f32_32x32x16_bf16 v[80:95], v[150:153], v[130:133], 0
	v_mfma_f32_32x32x16_bf16 v[64:79], v[154:157], v[130:133], 0
	global_load_dwordx4 v[134:137], v184, s[16:17]
	global_load_dwordx4 v[138:141], v184, s[2:3]
	global_load_dwordx4 v[142:145], v184, s[14:15]
	global_load_dwordx4 v[146:149], v184, s[10:11]
	s_add_u32 s16, s16, 0x60000
	s_addc_u32 s17, s17, 0
	s_add_u32 s2, s2, 0x60000
	s_addc_u32 s3, s3, 0
	s_add_u32 s14, s14, 0x60000
	s_addc_u32 s15, s15, 0
	s_add_u32 s10, s10, 0x60000
	s_addc_u32 s11, s11, 0
	ds_read_b128 v[150:153], v208 offset:0
	ds_read_b128 v[154:157], v208 offset:8192
	s_waitcnt lgkmcnt(10)
	v_mfma_f32_32x32x16_bf16 v[80:95], v[158:161], v[126:129], v[80:95]
	v_mfma_f32_32x32x16_bf16 v[64:79], v[162:165], v[126:129], v[64:79]
	ds_read_b128 v[158:161], v209 offset:0
	ds_read_b128 v[162:165], v209 offset:8192
	s_waitcnt lgkmcnt(10)
	v_mfma_f32_32x32x16_bf16 v[80:95], v[228:231], v[122:125], v[80:95]
	v_mfma_f32_32x32x16_bf16 v[64:79], v[232:235], v[122:125], v[64:79]
	ds_read_b128 v[228:231], v210 offset:0
	ds_read_b128 v[232:235], v210 offset:8192
	s_waitcnt lgkmcnt(10)
	v_mfma_f32_32x32x16_bf16 v[80:95], v[236:239], v[118:121], v[80:95]
	v_mfma_f32_32x32x16_bf16 v[64:79], v[240:243], v[118:121], v[64:79]
	ds_read_b128 v[236:239], v211 offset:0
	ds_read_b128 v[240:243], v211 offset:8192
	s_waitcnt lgkmcnt(6)
	v_mfma_f32_32x32x16_bf16 v[80:95], v[150:153], v[114:117], v[80:95]
	v_mfma_f32_32x32x16_bf16 v[64:79], v[154:157], v[114:117], v[64:79]
	s_waitcnt lgkmcnt(4)
	v_mfma_f32_32x32x16_bf16 v[80:95], v[158:161], v[110:113], v[80:95]
	v_mfma_f32_32x32x16_bf16 v[64:79], v[162:165], v[110:113], v[64:79]
	s_waitcnt lgkmcnt(2)
	v_mfma_f32_32x32x16_bf16 v[80:95], v[228:231], v[106:109], v[80:95]
	v_mfma_f32_32x32x16_bf16 v[64:79], v[232:235], v[106:109], v[64:79]
	s_waitcnt lgkmcnt(0)
	v_mfma_f32_32x32x16_bf16 v[80:95], v[236:239], v[102:105], v[80:95]
	v_mfma_f32_32x32x16_bf16 v[64:79], v[240:243], v[102:105], v[64:79]
	s_nop 12
	s_setprio 0
	s_branch .Lda_y0
.Lda_loop:
	s_setprio 3
	s_waitcnt vmcnt(4)
	ds_write_b128 v197, v[134:137] offset:32768
	ds_write_b128 v197, v[138:141] offset:40960
	ds_write_b128 v185, v[142:145] offset:32768
	ds_write_b128 v185, v[146:149] offset:40960
	s_waitcnt lgkmcnt(10)
	v_mfma_f32_32x32x16_bf16 v[80:95], v[150:153], v[130:133], 0
	v_mfma_f32_32x32x16_bf16 v[64:79], v[154:157], v[130:133], 0
	global_load_dwordx4 v[134:137], v184, s[16:17]
	global_load_dwordx4 v[138:141], v184, s[2:3]
	global_load_dwordx4 v[142:145], v184, s[14:15]
	global_load_dwordx4 v[146:149], v184, s[10:11]
	s_add_u32 s16, s16, 0x60000
	s_addc_u32 s17, s17, 0
	s_add_u32 s2, s2, 0x60000
	s_addc_u32 s3, s3, 0
	s_add_u32 s14, s14, 0x60000
	s_addc_u32 s15, s15, 0
	s_add_u32 s10, s10, 0x60000
	s_addc_u32 s11, s11, 0
	ds_read_b128 v[150:153], v208 offset:0
	ds_read_b128 v[154:157], v208 offset:8192
	s_waitcnt lgkmcnt(10)
	v_mfma_f32_32x32x16_bf16 v[80:95], v[158:161], v[126:129], v[80:95]
	v_mfma_f32_32x32x16_bf16 v[64:79], v[162:165], v[126:129], v[64:79]
	ds_read_b128 v[158:161], v209 offset:0
	ds_read_b128 v[162:165], v209 offset:8192
	s_waitcnt lgkmcnt(10)
	v_mfma_f32_32x32x16_bf16 v[80:95], v[228:231], v[122:125], v[80:95]
	v_mfma_f32_32x32x16_bf16 v[64:79], v[232:235], v[122:125], v[64:79]
	ds_read_b128 v[228:231], v210 offset:0
	ds_read_b128 v[232:235], v210 offset:8192
	s_waitcnt lgkmcnt(10)
	v_mfma_f32_32x32x16_bf16 v[80:95], v[236:239], v[118:121], v[80:95]
	v_mfma_f32_32x32x16_bf16 v[64:79], v[240:243], v[118:121], v[64:79]
	ds_read_b128 v[236:239], v211 offset:0
	ds_read_b128 v[240:243], v211 offset:8192
	s_waitcnt lgkmcnt(6)
	v_mfma_f32_32x32x16_bf16 v[80:95], v[150:153], v[114:117], v[80:95]
	v_mfma_f32_32x32x16_bf16 v[64:79], v[154:157], v[114:117], v[64:79]
	ds_read_b64_tr_b16 v[150:151], v196 offset:49152
	ds_read_b64_tr_b16 v[152:153], v196 offset:51200
	ds_read_b64_tr_b16 v[154:155], v196 offset:53248
	ds_read_b64_tr_b16 v[156:157], v196 offset:55296
	s_waitcnt lgkmcnt(8)
	v_mfma_f32_32x32x16_bf16 v[80:95], v[158:161], v[110:113], v[80:95]
	v_mfma_f32_32x32x16_bf16 v[64:79], v[162:165], v[110:113], v[64:79]
	ds_read_b64_tr_b16 v[158:159], v196 offset:57344
	ds_read_b64_tr_b16 v[160:161], v196 offset:59392
	ds_read_b64_tr_b16 v[162:163], v196 offset:61440
	ds_read_b64_tr_b16 v[164:165], v196 offset:63488
	s_waitcnt lgkmcnt(10)
	v_mfma_f32_32x32x16_bf16 v[80:95], v[228:231], v[106:109], v[80:95]
	v_mfma_f32_32x32x16_bf16 v[64:79], v[232:235], v[106:109], v[64:79]
	ds_read_b64_tr_b16 v[228:229], v196 offset:49664
	ds_read_b64_tr_b16 v[230:231], v196 offset:51712
	ds_read_b64_tr_b16 v[232:233], v196 offset:53760
	ds_read_b64_tr_b16 v[234:235], v196 offset:55808
	s_waitcnt lgkmcnt(12)
	v_mfma_f32_32x32x16_bf16 v[80:95], v[236:239], v[102:105], v[80:95]
	v_mfma_f32_32x32x16_bf16 v[64:79], v[240:243], v[102:105], v[64:79]
	ds_read_b64_tr_b16 v[236:237], v196 offset:57856
	ds_read_b64_tr_b16 v[238:239], v196 offset:59904
	s_waitcnt lgkmcnt(12)
	v_mfma_f32_32x32x16_bf16 v[0:15], v[166:169], v[150:153], v[0:15]
	ds_read_b64_tr_b16 v[240:241], v196 offset:61952
	ds_read_b64_tr_b16 v[242:243], v196 offset:64000
	s_waitcnt lgkmcnt(12)
	v_mfma_f32_32x32x16_bf16 v[0:15], v[170:173], v[154:157], v[0:15]
	ds_read_b64_tr_b16 v[150:151], v196 offset:50176
	ds_read_b64_tr_b16 v[152:153], v196 offset:52224
	s_waitcnt lgkmcnt(12)
; #define SBAR() __builtin_amdgcn_sched_barrier(0)
; __device__ __forceinline__ void partialSM(f32x16& p0, f32x16& p1, float& m_reg, float& mn, float& alpha) {
;   constexpr float C = SCALE * 1.4426950408889634f;
;   float pmax = p0[0];
; #pragma unroll
;   for (int r = 1; r < 16; ++r) pmax = fmaxf(pmax, p0[r]);
; #pragma unroll
;   for (int r = 0; r < 16; ++r) pmax = fmaxf(pmax, p1[r]);
;   { auto rr = __builtin_amdgcn_permlane32_swap(__float_as_uint(pmax), __float_as_uint(pmax), false, false);
;     pmax = fmaxf(__uint_as_float(rr[0]), __uint_as_float(rr[1])); }
;   if (__builtin_expect(__all(pmax - m_reg <= THR / SCALE), 1)) { mn = m_reg; alpha = 1.f; }
;   else { mn = fmaxf(m_reg, pmax); alpha = __builtin_amdgcn_exp2f((m_reg - mn) * C); m_reg = mn; }
;   float mnC = -mn * C;
; #pragma unroll
;   for (int r = 0; r < 16; ++r) p0[r] = fmaf(p0[r], C, mnC);
; #pragma unroll
;   for (int r = 0; r < 16; ++r) p1[r] = fmaf(p1[r], C, mnC);
; template <int D0> __device__ __forceinline__ void pv_one(f32x16& od, int vb, bf16x8 pa0, bf16x8 pa1, bf16x8 pa2, bf16x8 pa3) {
;   const s16x4 l0 = tr_read<v_rd_off(D0, 0, 0)>(vb), h0 = tr_read<v_rd_off(D0, 0, 1)>(vb), l1 = tr_read<v_rd_off(D0, 1, 0)>(vb), h1 = tr_read<v_rd_off(D0, 1, 1)>(vb);
;   const s16x4 l2 = tr_read<v_rd_off(D0, 2, 0)>(vb), h2 = tr_read<v_rd_off(D0, 2, 1)>(vb), l3 = tr_read<v_rd_off(D0, 3, 0)>(vb), h3 = tr_read<v_rd_off(D0, 3, 1)>(vb);
;   asm volatile("s_waitcnt lgkmcnt(0)" ::: "memory"); SBAR();
;     ...
;   od = __builtin_amdgcn_mfma_f32_32x32x16_bf16(pa0, PK(l0, h0), od, 0, 0, 0);
;   od = __builtin_amdgcn_mfma_f32_32x32x16_bf16(pa1, PK(l1, h1), od, 0, 0, 0);
;   od = __builtin_amdgcn_mfma_f32_32x32x16_bf16(pa2, PK(l2, h2), od, 0, 0, 0);
;   od = __builtin_amdgcn_mfma_f32_32x32x16_bf16(pa3, PK(l3, h3), od, 0, 0, 0);
;     ...
; }
; __device__ __forceinline__ void pv_d0(f32x16* o, int vb, bf16x8 pa0, bf16x8 pa1, bf16x8 pa2, bf16x8 pa3) {
;   pv_one<0>(o[0], vb, pa0, pa1, pa2, pa3); pv_one<1>(o[1], vb, pa0, pa1, pa2, pa3); pv_one<2>(o[2], vb, pa0, pa1, pa2, pa3); pv_one<3>(o[3], vb, pa0, pa1, pa2, pa3);
	v_mfma_f32_32x32x16_bf16 v[0:15], v[176:179], v[158:161], v[0:15]
	ds_read_b64_tr_b16 v[154:155], v196 offset:54272
	ds_read_b64_tr_b16 v[156:157], v196 offset:56320
	s_waitcnt lgkmcnt(12)
	v_mfma_f32_32x32x16_bf16 v[0:15], v[180:183], v[162:165], v[0:15]
	ds_read_b64_tr_b16 v[158:159], v196 offset:58368
	ds_read_b64_tr_b16 v[160:161], v196 offset:60416
	s_waitcnt lgkmcnt(12)
	v_mfma_f32_32x32x16_bf16 v[48:63], v[166:169], v[228:231], v[48:63]
	ds_read_b64_tr_b16 v[162:163], v196 offset:62464
	ds_read_b64_tr_b16 v[164:165], v196 offset:64512
	s_waitcnt lgkmcnt(12)
	v_mfma_f32_32x32x16_bf16 v[48:63], v[170:173], v[232:235], v[48:63]
	ds_read_b64_tr_b16 v[228:229], v196 offset:50688
	ds_read_b64_tr_b16 v[230:231], v196 offset:52736
	s_waitcnt lgkmcnt(12)
	v_mfma_f32_32x32x16_bf16 v[48:63], v[176:179], v[236:239], v[48:63]
	ds_read_b64_tr_b16 v[232:233], v196 offset:54784
	ds_read_b64_tr_b16 v[234:235], v196 offset:56832
	s_waitcnt lgkmcnt(12)
	v_mfma_f32_32x32x16_bf16 v[48:63], v[180:183], v[240:243], v[48:63]
	ds_read_b64_tr_b16 v[236:237], v196 offset:58880
	ds_read_b64_tr_b16 v[238:239], v196 offset:60928
	s_waitcnt lgkmcnt(12)
	v_mfma_f32_32x32x16_bf16 v[32:47], v[166:169], v[150:153], v[32:47]
	ds_read_b64_tr_b16 v[240:241], v196 offset:62976
	ds_read_b64_tr_b16 v[242:243], v196 offset:65024
	s_waitcnt lgkmcnt(12)
	v_mfma_f32_32x32x16_bf16 v[32:47], v[170:173], v[154:157], v[32:47]
	s_waitcnt lgkmcnt(10)
	v_mfma_f32_32x32x16_bf16 v[32:47], v[176:179], v[158:161], v[32:47]
	s_waitcnt lgkmcnt(8)
	v_mfma_f32_32x32x16_bf16 v[32:47], v[180:183], v[162:165], v[32:47]
	s_waitcnt lgkmcnt(6)
	v_mfma_f32_32x32x16_bf16 v[16:31], v[166:169], v[228:231], v[16:31]
	s_waitcnt lgkmcnt(4)
	v_mfma_f32_32x32x16_bf16 v[16:31], v[170:173], v[232:235], v[16:31]
	s_waitcnt lgkmcnt(2)
	v_mfma_f32_32x32x16_bf16 v[16:31], v[176:179], v[236:239], v[16:31]
	s_waitcnt lgkmcnt(0)
	v_mfma_f32_32x32x16_bf16 v[16:31], v[180:183], v[240:243], v[16:31]
	s_setprio 0
.Lda_y0:
	s_barrier
	v_max3_f32 v190, v80, v81, v82
	v_max3_f32 v191, v64, v65, v66
	v_max3_f32 v190, v190, v83, v84
	v_max3_f32 v191, v191, v67, v68
	v_max3_f32 v190, v190, v85, v86
	v_max3_f32 v191, v191, v69, v70
	v_max3_f32 v190, v190, v87, v88
	v_max3_f32 v191, v191, v71, v72
	v_max3_f32 v190, v190, v89, v90
	v_max3_f32 v191, v191, v73, v74
	v_max3_f32 v190, v190, v91, v92
	v_max3_f32 v191, v191, v75, v76
	v_max3_f32 v190, v190, v93, v94
	v_max3_f32 v191, v191, v77, v78
	v_max3_f32 v190, v190, v95, v79
	v_max_f32_e32 v190, v190, v191
	v_mov_b32_e32 v191, v190
	s_nop 1
	v_permlane32_swap_b32_e32 v190, v191
	s_nop 0
	v_max_f32_e32 v212, v190, v191
	v_sub_f32_e32 v190, v212, v174
	v_cmp_ge_f32_e32 vcc, s86, v190
	v_max_f32_e32 v191, v174, v212
	v_sub_f32_e32 v215, v174, v191
	v_mul_f32_e32 v215, s92, v215
	s_nop 1
	s_cmp_eq_u64 vcc, exec
	s_cselect_b64 s[42:43], -1, 0
	v_exp_f32_e32 v213, v215
	s_nop 0
	v_cndmask_b32_e64 v174, v191, v174, s[42:43]
	v_cndmask_b32_e64 v213, v213, 1.0, s[42:43]
	v_mul_f32_e32 v214, 0xbe0293ee, v174
	s_nop 0
	v_cmp_gt_f32_e32 vcc, 1.0, v213
	v_fma_f32 v80, v80, s92, v214
	v_fma_f32 v81, v81, s92, v214
	v_fma_f32 v82, v82, s92, v214
	v_fma_f32 v83, v83, s92, v214
	v_fma_f32 v84, v84, s92, v214
	v_fma_f32 v85, v85, s92, v214
	v_fma_f32 v86, v86, s92, v214
	v_fma_f32 v87, v87, s92, v214
	v_fma_f32 v88, v88, s92, v214
	v_fma_f32 v89, v89, s92, v214
	v_fma_f32 v90, v90, s92, v214
	v_fma_f32 v91, v91, s92, v214
	v_fma_f32 v92, v92, s92, v214
	v_fma_f32 v93, v93, s92, v214
	v_fma_f32 v94, v94, s92, v214
	v_fma_f32 v95, v95, s92, v214
	v_fma_f32 v64, v64, s92, v214
	v_fma_f32 v65, v65, s92, v214
	v_fma_f32 v66, v66, s92, v214
	v_fma_f32 v67, v67, s92, v214
	v_fma_f32 v68, v68, s92, v214
	v_fma_f32 v69, v69, s92, v214
	v_fma_f32 v70, v70, s92, v214
	v_fma_f32 v71, v71, s92, v214
	v_fma_f32 v72, v72, s92, v214
	v_fma_f32 v73, v73, s92, v214
	v_fma_f32 v74, v74, s92, v214
	v_fma_f32 v75, v75, s92, v214
	v_fma_f32 v76, v76, s92, v214
	v_fma_f32 v77, v77, s92, v214
	v_fma_f32 v78, v78, s92, v214
	v_fma_f32 v79, v79, s92, v214
	s_cbranch_vccz .Lda_noresc_0
	s_and_saveexec_b64 s[12:13], s[40:41]
	ds_write_b32 v199, v213 offset:128
	s_or_b64 exec, exec, s[12:13]
	s_waitcnt lgkmcnt(0)
	v_add_u32_e32 v215, v99, v96
	ds_read_b128 v[228:231], v215 offset:128
	ds_read_b128 v[232:235], v215 offset:160
	ds_read_b128 v[236:239], v215 offset:192
	ds_read_b128 v[240:243], v215 offset:224
	s_waitcnt lgkmcnt(0)
	v_pk_mul_f32 v[0:1], v[0:1], v[228:229]
	v_pk_mul_f32 v[2:3], v[2:3], v[230:231]
	v_pk_mul_f32 v[4:5], v[4:5], v[232:233]
	v_pk_mul_f32 v[6:7], v[6:7], v[234:235]
	v_pk_mul_f32 v[8:9], v[8:9], v[236:237]
	v_pk_mul_f32 v[10:11], v[10:11], v[238:239]
	v_pk_mul_f32 v[12:13], v[12:13], v[240:241]
	v_pk_mul_f32 v[14:15], v[14:15], v[242:243]
	v_pk_mul_f32 v[48:49], v[48:49], v[228:229]
	v_pk_mul_f32 v[50:51], v[50:51], v[230:231]
	v_pk_mul_f32 v[52:53], v[52:53], v[232:233]
	v_pk_mul_f32 v[54:55], v[54:55], v[234:235]
	v_pk_mul_f32 v[56:57], v[56:57], v[236:237]
	v_pk_mul_f32 v[58:59], v[58:59], v[238:239]
	v_pk_mul_f32 v[60:61], v[60:61], v[240:241]
	v_pk_mul_f32 v[62:63], v[62:63], v[242:243]
	v_pk_mul_f32 v[32:33], v[32:33], v[228:229]
	v_pk_mul_f32 v[34:35], v[34:35], v[230:231]
	v_pk_mul_f32 v[36:37], v[36:37], v[232:233]
	v_pk_mul_f32 v[38:39], v[38:39], v[234:235]
	v_pk_mul_f32 v[40:41], v[40:41], v[236:237]
	v_pk_mul_f32 v[42:43], v[42:43], v[238:239]
	v_pk_mul_f32 v[44:45], v[44:45], v[240:241]
	v_pk_mul_f32 v[46:47], v[46:47], v[242:243]
	v_pk_mul_f32 v[16:17], v[16:17], v[228:229]
	v_pk_mul_f32 v[18:19], v[18:19], v[230:231]
	v_pk_mul_f32 v[20:21], v[20:21], v[232:233]
	v_pk_mul_f32 v[22:23], v[22:23], v[234:235]
	v_pk_mul_f32 v[24:25], v[24:25], v[236:237]
	v_pk_mul_f32 v[26:27], v[26:27], v[238:239]
	v_pk_mul_f32 v[28:29], v[28:29], v[240:241]
	v_pk_mul_f32 v[30:31], v[30:31], v[242:243]

; #define SBAR() __builtin_amdgcn_sched_barrier(0)
; __device__ __forceinline__ void qkt(f32x16& p0, f32x16& p1, const bf16_t* Ks, const bf16x8* qr, int r32, int hi) {
;   p0 = f32x16{}; p1 = f32x16{};
; #pragma unroll
;   for (int d0 = 0; d0 < 8; ++d0) { int cb = (d0 * 16 + hi * 8) * 2;
;     bf16x8 b0 = *reinterpret_cast<const bf16x8*>((const char*)Ks + KSWZ(r32, cb));
;     bf16x8 b1 = *reinterpret_cast<const bf16x8*>((const char*)Ks + KSWZ(32 + r32, cb));
;     p0 = __builtin_amdgcn_mfma_f32_32x32x16_bf16(b0, qr[d0], p0, 0, 0, 0);
;     p1 = __builtin_amdgcn_mfma_f32_32x32x16_bf16(b1, qr[d0], p1, 0, 0, 0); }
; }
; __device__ __forceinline__ int v_st(int k, int c) { const int kk = (k & ~0xC) | ((k & 4) << 1) | ((k & 8) >> 1); return ((kk >> 3) * 4 + (c >> 5)) * 512 + ((kk & 7) * 32 + (c & 31)) * 2; }
; __device__ __forceinline__ int v_rd_base(int lane) { return ((lane & 3) << 3) | (((lane >> 2) & 3) << 6) | (((lane >> 4) & 1) << 5) | (((lane >> 5) & 1) << 8); }
; template <int OFF> __device__ __forceinline__ s16x4 tr_read(int vb) {
;   s16x4 r; asm volatile("ds_read_b64_tr_b16 %0, %1 offset:%2" : "=&v"(r) : "v"(vb), "i"(OFF) : "memory"); return r;
; }
; template <int D0> __device__ __forceinline__ void pv_one(f32x16& od, int vb, bf16x8 pa0, bf16x8 pa1, bf16x8 pa2, bf16x8 pa3) {
;   const s16x4 l0 = tr_read<v_rd_off(D0, 0, 0)>(vb), h0 = tr_read<v_rd_off(D0, 0, 1)>(vb), l1 = tr_read<v_rd_off(D0, 1, 0)>(vb), h1 = tr_read<v_rd_off(D0, 1, 1)>(vb);
;   const s16x4 l2 = tr_read<v_rd_off(D0, 2, 0)>(vb), h2 = tr_read<v_rd_off(D0, 2, 1)>(vb), l3 = tr_read<v_rd_off(D0, 3, 0)>(vb), h3 = tr_read<v_rd_off(D0, 3, 1)>(vb);
;   asm volatile("s_waitcnt lgkmcnt(0)" ::: "memory"); SBAR();
;     ...
;   od = __builtin_amdgcn_mfma_f32_32x32x16_bf16(pa0, PK(l0, h0), od, 0, 0, 0);
;   od = __builtin_amdgcn_mfma_f32_32x32x16_bf16(pa1, PK(l1, h1), od, 0, 0, 0);
;   od = __builtin_amdgcn_mfma_f32_32x32x16_bf16(pa2, PK(l2, h2), od, 0, 0, 0);
;   od = __builtin_amdgcn_mfma_f32_32x32x16_bf16(pa3, PK(l3, h3), od, 0, 0, 0);
;     ...
; }
; __device__ __forceinline__ void pv_d0(f32x16* o, int vb, bf16x8 pa0, bf16x8 pa1, bf16x8 pa2, bf16x8 pa3) {
;   pv_one<0>(o[0], vb, pa0, pa1, pa2, pa3); pv_one<1>(o[1], vb, pa0, pa1, pa2, pa3); pv_one<2>(o[2], vb, pa0, pa1, pa2, pa3); pv_one<3>(o[3], vb, pa0, pa1, pa2, pa3);
.Lda_skipk_0:
	s_barrier
	s_setprio 3
	s_waitcnt vmcnt(4)
	ds_write_b128 v197, v[186:189] offset:49152
	ds_write_b128 v197, v[220:223] offset:57344
	ds_write_b128 v185, v[246:249] offset:49152
	ds_write_b128 v185, v[200:203] offset:57344
	s_waitcnt lgkmcnt(10)
	v_mfma_f32_32x32x16_bf16 v[80:95], v[150:153], v[130:133], 0
	v_mfma_f32_32x32x16_bf16 v[64:79], v[154:157], v[130:133], 0
	global_load_dwordx4 v[186:189], v184, s[16:17]
	global_load_dwordx4 v[220:223], v184, s[2:3]
	global_load_dwordx4 v[246:249], v184, s[14:15]
	global_load_dwordx4 v[200:203], v184, s[10:11]
	s_add_u32 s16, s16, 0x60000
	s_addc_u32 s17, s17, 0
	s_add_u32 s2, s2, 0x60000
	s_addc_u32 s3, s3, 0
	s_add_u32 s14, s14, 0x60000
	s_addc_u32 s15, s15, 0
	s_add_u32 s10, s10, 0x60000
	s_addc_u32 s11, s11, 0
	ds_read_b128 v[150:153], v208 offset:16384
	ds_read_b128 v[154:157], v208 offset:24576
	s_waitcnt lgkmcnt(10)
	v_mfma_f32_32x32x16_bf16 v[80:95], v[158:161], v[126:129], v[80:95]
	v_mfma_f32_32x32x16_bf16 v[64:79], v[162:165], v[126:129], v[64:79]
	ds_read_b128 v[158:161], v209 offset:16384
	ds_read_b128 v[162:165], v209 offset:24576
	s_waitcnt lgkmcnt(10)
	v_mfma_f32_32x32x16_bf16 v[80:95], v[228:231], v[122:125], v[80:95]
	v_mfma_f32_32x32x16_bf16 v[64:79], v[232:235], v[122:125], v[64:79]
	ds_read_b128 v[228:231], v210 offset:16384
	ds_read_b128 v[232:235], v210 offset:24576
	s_waitcnt lgkmcnt(10)
	v_mfma_f32_32x32x16_bf16 v[80:95], v[236:239], v[118:121], v[80:95]
	v_mfma_f32_32x32x16_bf16 v[64:79], v[240:243], v[118:121], v[64:79]
	ds_read_b128 v[236:239], v211 offset:16384
	ds_read_b128 v[240:243], v211 offset:24576
	s_waitcnt lgkmcnt(6)
	v_mfma_f32_32x32x16_bf16 v[80:95], v[150:153], v[114:117], v[80:95]
	v_mfma_f32_32x32x16_bf16 v[64:79], v[154:157], v[114:117], v[64:79]
	ds_read_b64_tr_b16 v[150:151], v196 offset:0
	ds_read_b64_tr_b16 v[152:153], v196 offset:2048
	ds_read_b64_tr_b16 v[154:155], v196 offset:4096
	ds_read_b64_tr_b16 v[156:157], v196 offset:6144
	s_waitcnt lgkmcnt(8)
	v_mfma_f32_32x32x16_bf16 v[80:95], v[158:161], v[110:113], v[80:95]
	v_mfma_f32_32x32x16_bf16 v[64:79], v[162:165], v[110:113], v[64:79]
	ds_read_b64_tr_b16 v[158:159], v196 offset:8192
	ds_read_b64_tr_b16 v[160:161], v196 offset:10240
	ds_read_b64_tr_b16 v[162:163], v196 offset:12288
	ds_read_b64_tr_b16 v[164:165], v196 offset:14336
	s_waitcnt lgkmcnt(10)
	v_mfma_f32_32x32x16_bf16 v[80:95], v[228:231], v[106:109], v[80:95]
	v_mfma_f32_32x32x16_bf16 v[64:79], v[232:235], v[106:109], v[64:79]
	ds_read_b64_tr_b16 v[228:229], v196 offset:512
	ds_read_b64_tr_b16 v[230:231], v196 offset:2560
	ds_read_b64_tr_b16 v[232:233], v196 offset:4608
	ds_read_b64_tr_b16 v[234:235], v196 offset:6656
	s_waitcnt lgkmcnt(12)
	v_mfma_f32_32x32x16_bf16 v[80:95], v[236:239], v[102:105], v[80:95]
	v_mfma_f32_32x32x16_bf16 v[64:79], v[240:243], v[102:105], v[64:79]
	ds_read_b64_tr_b16 v[236:237], v196 offset:8704
	ds_read_b64_tr_b16 v[238:239], v196 offset:10752
	s_waitcnt lgkmcnt(12)
	v_mfma_f32_32x32x16_bf16 v[0:15], v[166:169], v[150:153], v[0:15]
	ds_read_b64_tr_b16 v[240:241], v196 offset:12800
	ds_read_b64_tr_b16 v[242:243], v196 offset:14848
	s_waitcnt lgkmcnt(12)
	v_mfma_f32_32x32x16_bf16 v[0:15], v[170:173], v[154:157], v[0:15]
	ds_read_b64_tr_b16 v[150:151], v196 offset:1024
	ds_read_b64_tr_b16 v[152:153], v196 offset:3072
	s_waitcnt lgkmcnt(12)
	v_mfma_f32_32x32x16_bf16 v[0:15], v[176:179], v[158:161], v[0:15]
	ds_read_b64_tr_b16 v[154:155], v196 offset:5120
	ds_read_b64_tr_b16 v[156:157], v196 offset:7168
	s_waitcnt lgkmcnt(12)
	v_mfma_f32_32x32x16_bf16 v[0:15], v[180:183], v[162:165], v[0:15]
	ds_read_b64_tr_b16 v[158:159], v196 offset:9216
	ds_read_b64_tr_b16 v[160:161], v196 offset:11264
	s_waitcnt lgkmcnt(12)
	v_mfma_f32_32x32x16_bf16 v[48:63], v[166:169], v[228:231], v[48:63]
	ds_read_b64_tr_b16 v[162:163], v196 offset:13312
	ds_read_b64_tr_b16 v[164:165], v196 offset:15360
	s_waitcnt lgkmcnt(12)
	v_mfma_f32_32x32x16_bf16 v[48:63], v[170:173], v[232:235], v[48:63]
	ds_read_b64_tr_b16 v[228:229], v196 offset:1536
	ds_read_b64_tr_b16 v[230:231], v196 offset:3584
	s_waitcnt lgkmcnt(12)
	v_mfma_f32_32x32x16_bf16 v[48:63], v[176:179], v[236:239], v[48:63]
	ds_read_b64_tr_b16 v[232:233], v196 offset:5632
	ds_read_b64_tr_b16 v[234:235], v196 offset:7680
	s_waitcnt lgkmcnt(12)
	v_mfma_f32_32x32x16_bf16 v[48:63], v[180:183], v[240:243], v[48:63]
	ds_read_b64_tr_b16 v[236:237], v196 offset:9728
	ds_read_b64_tr_b16 v[238:239], v196 offset:11776
	s_waitcnt lgkmcnt(12)
	v_mfma_f32_32x32x16_bf16 v[32:47], v[166:169], v[150:153], v[32:47]
	ds_read_b64_tr_b16 v[240:241], v196 offset:13824
	ds_read_b64_tr_b16 v[242:243], v196 offset:15872
	s_waitcnt lgkmcnt(12)
	v_mfma_f32_32x32x16_bf16 v[32:47], v[170:173], v[154:157], v[32:47]
	s_waitcnt lgkmcnt(10)
	v_mfma_f32_32x32x16_bf16 v[32:47], v[176:179], v[158:161], v[32:47]
	s_waitcnt lgkmcnt(8)
	v_mfma_f32_32x32x16_bf16 v[32:47], v[180:183], v[162:165], v[32:47]
	s_waitcnt lgkmcnt(6)
	v_mfma_f32_32x32x16_bf16 v[16:31], v[166:169], v[228:231], v[16:31]
	s_waitcnt lgkmcnt(4)
	v_mfma_f32_32x32x16_bf16 v[16:31], v[170:173], v[232:235], v[16:31]
	s_waitcnt lgkmcnt(2)
	v_mfma_f32_32x32x16_bf16 v[16:31], v[176:179], v[236:239], v[16:31]
	s_waitcnt lgkmcnt(0)
	v_mfma_f32_32x32x16_bf16 v[16:31], v[180:183], v[240:243], v[16:31]
	s_setprio 0
	s_barrier
; __device__ __forceinline__ void partialSM(f32x16& p0, f32x16& p1, float& m_reg, float& mn, float& alpha) {
;   constexpr float C = SCALE * 1.4426950408889634f;
;   float pmax = p0[0];
; #pragma unroll
;   for (int r = 1; r < 16; ++r) pmax = fmaxf(pmax, p0[r]);
; #pragma unroll
;   for (int r = 0; r < 16; ++r) pmax = fmaxf(pmax, p1[r]);
;   { auto rr = __builtin_amdgcn_permlane32_swap(__float_as_uint(pmax), __float_as_uint(pmax), false, false);
;     pmax = fmaxf(__uint_as_float(rr[0]), __uint_as_float(rr[1])); }
;   if (__builtin_expect(__all(pmax - m_reg <= THR / SCALE), 1)) { mn = m_reg; alpha = 1.f; }
;   else { mn = fmaxf(m_reg, pmax); alpha = __builtin_amdgcn_exp2f((m_reg - mn) * C); m_reg = mn; }
;   float mnC = -mn * C;
; #pragma unroll
;   for (int r = 0; r < 16; ++r) p0[r] = fmaf(p0[r], C, mnC);
; #pragma unroll
;   for (int r = 0; r < 16; ++r) p1[r] = fmaf(p1[r], C, mnC);
	v_max3_f32 v190, v80, v81, v82
	v_max3_f32 v191, v64, v65, v66
	v_max3_f32 v190, v190, v83, v84
	v_max3_f32 v191, v191, v67, v68
	v_max3_f32 v190, v190, v85, v86
	v_max3_f32 v191, v191, v69, v70
	v_max3_f32 v190, v190, v87, v88
	v_max3_f32 v191, v191, v71, v72
	v_max3_f32 v190, v190, v89, v90
	v_max3_f32 v191, v191, v73, v74
	v_max3_f32 v190, v190, v91, v92
	v_max3_f32 v191, v191, v75, v76
	v_max3_f32 v190, v190, v93, v94
	v_max3_f32 v191, v191, v77, v78
	v_max3_f32 v190, v190, v95, v79
	v_max_f32_e32 v190, v190, v191
	v_mov_b32_e32 v191, v190
	s_nop 1
	v_permlane32_swap_b32_e32 v190, v191
	s_nop 0
	v_max_f32_e32 v212, v190, v191
	v_sub_f32_e32 v190, v212, v174
	v_cmp_ge_f32_e32 vcc, s86, v190
	v_max_f32_e32 v191, v174, v212
	v_sub_f32_e32 v215, v174, v191
	v_mul_f32_e32 v215, s92, v215
	s_nop 1
	s_cmp_eq_u64 vcc, exec
	s_cselect_b64 s[42:43], -1, 0
	v_exp_f32_e32 v213, v215
	s_nop 0
	v_cndmask_b32_e64 v174, v191, v174, s[42:43]
	v_cndmask_b32_e64 v213, v213, 1.0, s[42:43]
	v_mul_f32_e32 v214, 0xbe0293ee, v174
	s_nop 0
	v_cmp_gt_f32_e32 vcc, 1.0, v213
	v_fma_f32 v80, v80, s92, v214
	v_fma_f32 v81, v81, s92, v214
	v_fma_f32 v82, v82, s92, v214
	v_fma_f32 v83, v83, s92, v214
	v_fma_f32 v84, v84, s92, v214
	v_fma_f32 v85, v85, s92, v214
	v_fma_f32 v86, v86, s92, v214
	v_fma_f32 v87, v87, s92, v214
	v_fma_f32 v88, v88, s92, v214
	v_fma_f32 v89, v89, s92, v214
	v_fma_f32 v90, v90, s92, v214
	v_fma_f32 v91, v91, s92, v214
	v_fma_f32 v92, v92, s92, v214
	v_fma_f32 v93, v93, s92, v214
	v_fma_f32 v94, v94, s92, v214
	v_fma_f32 v95, v95, s92, v214
	v_fma_f32 v64, v64, s92, v214
	v_fma_f32 v65, v65, s92, v214
	v_fma_f32 v66, v66, s92, v214
	v_fma_f32 v67, v67, s92, v214
	v_fma_f32 v68, v68, s92, v214
	v_fma_f32 v69, v69, s92, v214
	v_fma_f32 v70, v70, s92, v214
	v_fma_f32 v71, v71, s92, v214
	v_fma_f32 v72, v72, s92, v214
	v_fma_f32 v73, v73, s92, v214
	v_fma_f32 v74, v74, s92, v214
	v_fma_f32 v75, v75, s92, v214
	v_fma_f32 v76, v76, s92, v214
	v_fma_f32 v77, v77, s92, v214
	v_fma_f32 v78, v78, s92, v214
	v_fma_f32 v79, v79, s92, v214
	s_cbranch_vccz .Lda_noresc_1
	s_and_saveexec_b64 s[12:13], s[40:41]
	ds_write_b32 v199, v213 offset:128
	s_or_b64 exec, exec, s[12:13]
	s_waitcnt lgkmcnt(0)
	v_add_u32_e32 v215, v99, v96
	ds_read_b128 v[228:231], v215 offset:128
	ds_read_b128 v[232:235], v215 offset:160
	ds_read_b128 v[236:239], v215 offset:192
	ds_read_b128 v[240:243], v215 offset:224
	s_waitcnt lgkmcnt(0)
	v_pk_mul_f32 v[0:1], v[0:1], v[228:229]
	v_pk_mul_f32 v[2:3], v[2:3], v[230:231]
	v_pk_mul_f32 v[4:5], v[4:5], v[232:233]
	v_pk_mul_f32 v[6:7], v[6:7], v[234:235]
	v_pk_mul_f32 v[8:9], v[8:9], v[236:237]
	v_pk_mul_f32 v[10:11], v[10:11], v[238:239]
	v_pk_mul_f32 v[12:13], v[12:13], v[240:241]
	v_pk_mul_f32 v[14:15], v[14:15], v[242:243]
	v_pk_mul_f32 v[48:49], v[48:49], v[228:229]
	v_pk_mul_f32 v[50:51], v[50:51], v[230:231]
	v_pk_mul_f32 v[52:53], v[52:53], v[232:233]
	v_pk_mul_f32 v[54:55], v[54:55], v[234:235]
	v_pk_mul_f32 v[56:57], v[56:57], v[236:237]
	v_pk_mul_f32 v[58:59], v[58:59], v[238:239]
	v_pk_mul_f32 v[60:61], v[60:61], v[240:241]
	v_pk_mul_f32 v[62:63], v[62:63], v[242:243]
	v_pk_mul_f32 v[32:33], v[32:33], v[228:229]
	v_pk_mul_f32 v[34:35], v[34:35], v[230:231]
	v_pk_mul_f32 v[36:37], v[36:37], v[232:233]
	v_pk_mul_f32 v[38:39], v[38:39], v[234:235]
	v_pk_mul_f32 v[40:41], v[40:41], v[236:237]
	v_pk_mul_f32 v[42:43], v[42:43], v[238:239]
	v_pk_mul_f32 v[44:45], v[44:45], v[240:241]
	v_pk_mul_f32 v[46:47], v[46:47], v[242:243]
	v_pk_mul_f32 v[16:17], v[16:17], v[228:229]
	v_pk_mul_f32 v[18:19], v[18:19], v[230:231]
	v_pk_mul_f32 v[20:21], v[20:21], v[232:233]
	v_pk_mul_f32 v[22:23], v[22:23], v[234:235]
	v_pk_mul_f32 v[24:25], v[24:25], v[236:237]
	v_pk_mul_f32 v[26:27], v[26:27], v[238:239]
	v_pk_mul_f32 v[28:29], v[28:29], v[240:241]
	v_pk_mul_f32 v[30:31], v[30:31], v[242:243]

; #define SBAR() __builtin_amdgcn_sched_barrier(0)
; __device__ __forceinline__ void qkt(f32x16& p0, f32x16& p1, const bf16_t* Ks, const bf16x8* qr, int r32, int hi) {
;   p0 = f32x16{}; p1 = f32x16{};
; #pragma unroll
;   for (int d0 = 0; d0 < 8; ++d0) { int cb = (d0 * 16 + hi * 8) * 2;
;     bf16x8 b0 = *reinterpret_cast<const bf16x8*>((const char*)Ks + KSWZ(r32, cb));
;     bf16x8 b1 = *reinterpret_cast<const bf16x8*>((const char*)Ks + KSWZ(32 + r32, cb));
;     p0 = __builtin_amdgcn_mfma_f32_32x32x16_bf16(b0, qr[d0], p0, 0, 0, 0);
;     p1 = __builtin_amdgcn_mfma_f32_32x32x16_bf16(b1, qr[d0], p1, 0, 0, 0); }
; }
; __device__ __forceinline__ int v_st(int k, int c) { const int kk = (k & ~0xC) | ((k & 4) << 1) | ((k & 8) >> 1); return ((kk >> 3) * 4 + (c >> 5)) * 512 + ((kk & 7) * 32 + (c & 31)) * 2; }
; __device__ __forceinline__ int v_rd_base(int lane) { return ((lane & 3) << 3) | (((lane >> 2) & 3) << 6) | (((lane >> 4) & 1) << 5) | (((lane >> 5) & 1) << 8); }
; template <int OFF> __device__ __forceinline__ s16x4 tr_read(int vb) {
;   s16x4 r; asm volatile("ds_read_b64_tr_b16 %0, %1 offset:%2" : "=&v"(r) : "v"(vb), "i"(OFF) : "memory"); return r;
; }
; template <int D0> __device__ __forceinline__ void pv_one(f32x16& od, int vb, bf16x8 pa0, bf16x8 pa1, bf16x8 pa2, bf16x8 pa3) {
;   const s16x4 l0 = tr_read<v_rd_off(D0, 0, 0)>(vb), h0 = tr_read<v_rd_off(D0, 0, 1)>(vb), l1 = tr_read<v_rd_off(D0, 1, 0)>(vb), h1 = tr_read<v_rd_off(D0, 1, 1)>(vb);
;   const s16x4 l2 = tr_read<v_rd_off(D0, 2, 0)>(vb), h2 = tr_read<v_rd_off(D0, 2, 1)>(vb), l3 = tr_read<v_rd_off(D0, 3, 0)>(vb), h3 = tr_read<v_rd_off(D0, 3, 1)>(vb);
;   asm volatile("s_waitcnt lgkmcnt(0)" ::: "memory"); SBAR();
;     ...
;   od = __builtin_amdgcn_mfma_f32_32x32x16_bf16(pa0, PK(l0, h0), od, 0, 0, 0);
;   od = __builtin_amdgcn_mfma_f32_32x32x16_bf16(pa1, PK(l1, h1), od, 0, 0, 0);
;   od = __builtin_amdgcn_mfma_f32_32x32x16_bf16(pa2, PK(l2, h2), od, 0, 0, 0);
;   od = __builtin_amdgcn_mfma_f32_32x32x16_bf16(pa3, PK(l3, h3), od, 0, 0, 0);
;     ...
; }
; __device__ __forceinline__ void pv_d0(f32x16* o, int vb, bf16x8 pa0, bf16x8 pa1, bf16x8 pa2, bf16x8 pa3) {
;   pv_one<0>(o[0], vb, pa0, pa1, pa2, pa3); pv_one<1>(o[1], vb, pa0, pa1, pa2, pa3); pv_one<2>(o[2], vb, pa0, pa1, pa2, pa3); pv_one<3>(o[3], vb, pa0, pa1, pa2, pa3);
.Lda_skipk_1:
	s_barrier
	s_setprio 3
	s_waitcnt vmcnt(4)
	ds_write_b128 v197, v[134:137] offset:0
	ds_write_b128 v197, v[138:141] offset:8192
	ds_write_b128 v185, v[142:145] offset:0
	ds_write_b128 v185, v[146:149] offset:8192
	s_waitcnt lgkmcnt(10)
	v_mfma_f32_32x32x16_bf16 v[80:95], v[150:153], v[130:133], 0
	v_mfma_f32_32x32x16_bf16 v[64:79], v[154:157], v[130:133], 0
	global_load_dwordx4 v[134:137], v184, s[16:17]
	global_load_dwordx4 v[138:141], v184, s[2:3]
	global_load_dwordx4 v[142:145], v184, s[14:15]
	global_load_dwordx4 v[146:149], v184, s[10:11]
	s_add_u32 s16, s16, 0x60000
	s_addc_u32 s17, s17, 0
	s_add_u32 s2, s2, 0x60000
	s_addc_u32 s3, s3, 0
	s_add_u32 s14, s14, 0x60000
	s_addc_u32 s15, s15, 0
	s_add_u32 s10, s10, 0x60000
	s_addc_u32 s11, s11, 0
	ds_read_b128 v[150:153], v208 offset:32768
	ds_read_b128 v[154:157], v208 offset:40960
	s_waitcnt lgkmcnt(10)
	v_mfma_f32_32x32x16_bf16 v[80:95], v[158:161], v[126:129], v[80:95]
	v_mfma_f32_32x32x16_bf16 v[64:79], v[162:165], v[126:129], v[64:79]
	ds_read_b128 v[158:161], v209 offset:32768
	ds_read_b128 v[162:165], v209 offset:40960
	s_waitcnt lgkmcnt(10)
	v_mfma_f32_32x32x16_bf16 v[80:95], v[228:231], v[122:125], v[80:95]
	v_mfma_f32_32x32x16_bf16 v[64:79], v[232:235], v[122:125], v[64:79]
	ds_read_b128 v[228:231], v210 offset:32768
	ds_read_b128 v[232:235], v210 offset:40960
	s_waitcnt lgkmcnt(10)
	v_mfma_f32_32x32x16_bf16 v[80:95], v[236:239], v[118:121], v[80:95]
	v_mfma_f32_32x32x16_bf16 v[64:79], v[240:243], v[118:121], v[64:79]
	ds_read_b128 v[236:239], v211 offset:32768
	ds_read_b128 v[240:243], v211 offset:40960
	s_waitcnt lgkmcnt(6)
	v_mfma_f32_32x32x16_bf16 v[80:95], v[150:153], v[114:117], v[80:95]
	v_mfma_f32_32x32x16_bf16 v[64:79], v[154:157], v[114:117], v[64:79]
	ds_read_b64_tr_b16 v[150:151], v196 offset:16384
	ds_read_b64_tr_b16 v[152:153], v196 offset:18432
	ds_read_b64_tr_b16 v[154:155], v196 offset:20480
	ds_read_b64_tr_b16 v[156:157], v196 offset:22528
	s_waitcnt lgkmcnt(8)
	v_mfma_f32_32x32x16_bf16 v[80:95], v[158:161], v[110:113], v[80:95]
	v_mfma_f32_32x32x16_bf16 v[64:79], v[162:165], v[110:113], v[64:79]
	ds_read_b64_tr_b16 v[158:159], v196 offset:24576
	ds_read_b64_tr_b16 v[160:161], v196 offset:26624
	ds_read_b64_tr_b16 v[162:163], v196 offset:28672
	ds_read_b64_tr_b16 v[164:165], v196 offset:30720
	s_waitcnt lgkmcnt(10)
	v_mfma_f32_32x32x16_bf16 v[80:95], v[228:231], v[106:109], v[80:95]
	v_mfma_f32_32x32x16_bf16 v[64:79], v[232:235], v[106:109], v[64:79]
	ds_read_b64_tr_b16 v[228:229], v196 offset:16896
	ds_read_b64_tr_b16 v[230:231], v196 offset:18944
	ds_read_b64_tr_b16 v[232:233], v196 offset:20992
	ds_read_b64_tr_b16 v[234:235], v196 offset:23040
	s_waitcnt lgkmcnt(12)
	v_mfma_f32_32x32x16_bf16 v[80:95], v[236:239], v[102:105], v[80:95]
	v_mfma_f32_32x32x16_bf16 v[64:79], v[240:243], v[102:105], v[64:79]
	ds_read_b64_tr_b16 v[236:237], v196 offset:25088
	ds_read_b64_tr_b16 v[238:239], v196 offset:27136
	s_waitcnt lgkmcnt(12)
	v_mfma_f32_32x32x16_bf16 v[0:15], v[166:169], v[150:153], v[0:15]
	ds_read_b64_tr_b16 v[240:241], v196 offset:29184
	ds_read_b64_tr_b16 v[242:243], v196 offset:31232
	s_waitcnt lgkmcnt(12)
	v_mfma_f32_32x32x16_bf16 v[0:15], v[170:173], v[154:157], v[0:15]
	ds_read_b64_tr_b16 v[150:151], v196 offset:17408
	ds_read_b64_tr_b16 v[152:153], v196 offset:19456
	s_waitcnt lgkmcnt(12)
	v_mfma_f32_32x32x16_bf16 v[0:15], v[176:179], v[158:161], v[0:15]
	ds_read_b64_tr_b16 v[154:155], v196 offset:21504
	ds_read_b64_tr_b16 v[156:157], v196 offset:23552
	s_waitcnt lgkmcnt(12)
	v_mfma_f32_32x32x16_bf16 v[0:15], v[180:183], v[162:165], v[0:15]
	ds_read_b64_tr_b16 v[158:159], v196 offset:25600
	ds_read_b64_tr_b16 v[160:161], v196 offset:27648
	s_waitcnt lgkmcnt(12)
	v_mfma_f32_32x32x16_bf16 v[48:63], v[166:169], v[228:231], v[48:63]
	ds_read_b64_tr_b16 v[162:163], v196 offset:29696
	ds_read_b64_tr_b16 v[164:165], v196 offset:31744
	s_waitcnt lgkmcnt(12)
	v_mfma_f32_32x32x16_bf16 v[48:63], v[170:173], v[232:235], v[48:63]
	ds_read_b64_tr_b16 v[228:229], v196 offset:17920
	ds_read_b64_tr_b16 v[230:231], v196 offset:19968
	s_waitcnt lgkmcnt(12)
	v_mfma_f32_32x32x16_bf16 v[48:63], v[176:179], v[236:239], v[48:63]
	ds_read_b64_tr_b16 v[232:233], v196 offset:22016
	ds_read_b64_tr_b16 v[234:235], v196 offset:24064
	s_waitcnt lgkmcnt(12)
	v_mfma_f32_32x32x16_bf16 v[48:63], v[180:183], v[240:243], v[48:63]
	ds_read_b64_tr_b16 v[236:237], v196 offset:26112
	ds_read_b64_tr_b16 v[238:239], v196 offset:28160
	s_waitcnt lgkmcnt(12)
	v_mfma_f32_32x32x16_bf16 v[32:47], v[166:169], v[150:153], v[32:47]
	ds_read_b64_tr_b16 v[240:241], v196 offset:30208
	ds_read_b64_tr_b16 v[242:243], v196 offset:32256
	s_waitcnt lgkmcnt(12)
	v_mfma_f32_32x32x16_bf16 v[32:47], v[170:173], v[154:157], v[32:47]
	s_waitcnt lgkmcnt(10)
	v_mfma_f32_32x32x16_bf16 v[32:47], v[176:179], v[158:161], v[32:47]
	s_waitcnt lgkmcnt(8)
	v_mfma_f32_32x32x16_bf16 v[32:47], v[180:183], v[162:165], v[32:47]
	s_waitcnt lgkmcnt(6)
	v_mfma_f32_32x32x16_bf16 v[16:31], v[166:169], v[228:231], v[16:31]
	s_waitcnt lgkmcnt(4)
	v_mfma_f32_32x32x16_bf16 v[16:31], v[170:173], v[232:235], v[16:31]
	s_waitcnt lgkmcnt(2)
	v_mfma_f32_32x32x16_bf16 v[16:31], v[176:179], v[236:239], v[16:31]
	s_waitcnt lgkmcnt(0)
	v_mfma_f32_32x32x16_bf16 v[16:31], v[180:183], v[240:243], v[16:31]
	s_setprio 0
	s_barrier
; __device__ __forceinline__ void partialSM(f32x16& p0, f32x16& p1, float& m_reg, float& mn, float& alpha) {
;   constexpr float C = SCALE * 1.4426950408889634f;
;   float pmax = p0[0];
; #pragma unroll
;   for (int r = 1; r < 16; ++r) pmax = fmaxf(pmax, p0[r]);
; #pragma unroll
;   for (int r = 0; r < 16; ++r) pmax = fmaxf(pmax, p1[r]);
;   { auto rr = __builtin_amdgcn_permlane32_swap(__float_as_uint(pmax), __float_as_uint(pmax), false, false);
;     pmax = fmaxf(__uint_as_float(rr[0]), __uint_as_float(rr[1])); }
;   if (__builtin_expect(__all(pmax - m_reg <= THR / SCALE), 1)) { mn = m_reg; alpha = 1.f; }
;   else { mn = fmaxf(m_reg, pmax); alpha = __builtin_amdgcn_exp2f((m_reg - mn) * C); m_reg = mn; }
;   float mnC = -mn * C;
; #pragma unroll
;   for (int r = 0; r < 16; ++r) p0[r] = fmaf(p0[r], C, mnC);
; #pragma unroll
;   for (int r = 0; r < 16; ++r) p1[r] = fmaf(p1[r], C, mnC);
; #pragma unroll
;   for (int r = 0; r < 16; ++r) p0[r] = __builtin_amdgcn_exp2f(p0[r]);
; }
	v_max3_f32 v190, v80, v81, v82
	v_max3_f32 v191, v64, v65, v66
	v_max3_f32 v190, v190, v83, v84
	v_max3_f32 v191, v191, v67, v68
	v_max3_f32 v190, v190, v85, v86
	v_max3_f32 v191, v191, v69, v70
	v_max3_f32 v190, v190, v87, v88
	v_max3_f32 v191, v191, v71, v72
	v_max3_f32 v190, v190, v89, v90
	v_max3_f32 v191, v191, v73, v74
	v_max3_f32 v190, v190, v91, v92
	v_max3_f32 v191, v191, v75, v76
	v_max3_f32 v190, v190, v93, v94
	v_max3_f32 v191, v191, v77, v78
	v_max3_f32 v190, v190, v95, v79
	v_max_f32_e32 v190, v190, v191
	v_mov_b32_e32 v191, v190
	s_nop 1
	v_permlane32_swap_b32_e32 v190, v191
	s_nop 0
	v_max_f32_e32 v212, v190, v191
	v_sub_f32_e32 v190, v212, v174
	v_cmp_ge_f32_e32 vcc, s86, v190
	v_max_f32_e32 v191, v174, v212
	v_sub_f32_e32 v215, v174, v191
	v_mul_f32_e32 v215, s92, v215
	s_nop 1
	s_cmp_eq_u64 vcc, exec
	s_cselect_b64 s[42:43], -1, 0
	v_exp_f32_e32 v213, v215
	s_nop 0
	v_cndmask_b32_e64 v174, v191, v174, s[42:43]
	v_cndmask_b32_e64 v213, v213, 1.0, s[42:43]
	v_mul_f32_e32 v214, 0xbe0293ee, v174
	s_nop 0
	v_cmp_gt_f32_e32 vcc, 1.0, v213
	v_fma_f32 v80, v80, s92, v214
	v_fma_f32 v81, v81, s92, v214
	v_fma_f32 v82, v82, s92, v214
	v_fma_f32 v83, v83, s92, v214
	v_fma_f32 v84, v84, s92, v214
	v_fma_f32 v85, v85, s92, v214
	v_fma_f32 v86, v86, s92, v214
	v_fma_f32 v87, v87, s92, v214
	v_fma_f32 v88, v88, s92, v214
	v_fma_f32 v89, v89, s92, v214
	v_fma_f32 v90, v90, s92, v214
	v_fma_f32 v91, v91, s92, v214
	v_fma_f32 v92, v92, s92, v214
	v_fma_f32 v93, v93, s92, v214
	v_fma_f32 v94, v94, s92, v214
	v_fma_f32 v95, v95, s92, v214
	v_fma_f32 v64, v64, s92, v214
	v_fma_f32 v65, v65, s92, v214
	v_fma_f32 v66, v66, s92, v214
	v_fma_f32 v67, v67, s92, v214
	v_fma_f32 v68, v68, s92, v214
	v_fma_f32 v69, v69, s92, v214
	v_fma_f32 v70, v70, s92, v214
	v_fma_f32 v71, v71, s92, v214
	v_fma_f32 v72, v72, s92, v214
	v_fma_f32 v73, v73, s92, v214
	v_fma_f32 v74, v74, s92, v214
	v_fma_f32 v75, v75, s92, v214
	v_fma_f32 v76, v76, s92, v214
	v_fma_f32 v77, v77, s92, v214
	v_fma_f32 v78, v78, s92, v214
	v_fma_f32 v79, v79, s92, v214
	s_cbranch_vccz .Lda_noresc_2
	s_and_saveexec_b64 s[12:13], s[40:41]
	ds_write_b32 v199, v213 offset:128
	s_or_b64 exec, exec, s[12:13]
	s_waitcnt lgkmcnt(0)
	v_add_u32_e32 v215, v99, v96
	ds_read_b128 v[228:231], v215 offset:128
	ds_read_b128 v[232:235], v215 offset:160
	ds_read_b128 v[236:239], v215 offset:192
	ds_read_b128 v[240:243], v215 offset:224
	s_waitcnt lgkmcnt(0)
	v_pk_mul_f32 v[0:1], v[0:1], v[228:229]
	v_pk_mul_f32 v[2:3], v[2:3], v[230:231]
	v_pk_mul_f32 v[4:5], v[4:5], v[232:233]
	v_pk_mul_f32 v[6:7], v[6:7], v[234:235]
	v_pk_mul_f32 v[8:9], v[8:9], v[236:237]
	v_pk_mul_f32 v[10:11], v[10:11], v[238:239]
	v_pk_mul_f32 v[12:13], v[12:13], v[240:241]
	v_pk_mul_f32 v[14:15], v[14:15], v[242:243]
	v_pk_mul_f32 v[48:49], v[48:49], v[228:229]
	v_pk_mul_f32 v[50:51], v[50:51], v[230:231]
	v_pk_mul_f32 v[52:53], v[52:53], v[232:233]
	v_pk_mul_f32 v[54:55], v[54:55], v[234:235]
	v_pk_mul_f32 v[56:57], v[56:57], v[236:237]
	v_pk_mul_f32 v[58:59], v[58:59], v[238:239]
	v_pk_mul_f32 v[60:61], v[60:61], v[240:241]
	v_pk_mul_f32 v[62:63], v[62:63], v[242:243]
	v_pk_mul_f32 v[32:33], v[32:33], v[228:229]
	v_pk_mul_f32 v[34:35], v[34:35], v[230:231]
	v_pk_mul_f32 v[36:37], v[36:37], v[232:233]
	v_pk_mul_f32 v[38:39], v[38:39], v[234:235]
	v_pk_mul_f32 v[40:41], v[40:41], v[236:237]
	v_pk_mul_f32 v[42:43], v[42:43], v[238:239]
	v_pk_mul_f32 v[44:45], v[44:45], v[240:241]
	v_pk_mul_f32 v[46:47], v[46:47], v[242:243]
	v_pk_mul_f32 v[16:17], v[16:17], v[228:229]
	v_pk_mul_f32 v[18:19], v[18:19], v[230:231]
	v_pk_mul_f32 v[20:21], v[20:21], v[232:233]
	v_pk_mul_f32 v[22:23], v[22:23], v[234:235]
	v_pk_mul_f32 v[24:25], v[24:25], v[236:237]
	v_pk_mul_f32 v[26:27], v[26:27], v[238:239]
	v_pk_mul_f32 v[28:29], v[28:29], v[240:241]
	v_pk_mul_f32 v[30:31], v[30:31], v[242:243]

; #define SBAR() __builtin_amdgcn_sched_barrier(0)
; __device__ __forceinline__ void qkt(f32x16& p0, f32x16& p1, const bf16_t* Ks, const bf16x8* qr, int r32, int hi) {
;   p0 = f32x16{}; p1 = f32x16{};
; #pragma unroll
;   for (int d0 = 0; d0 < 8; ++d0) { int cb = (d0 * 16 + hi * 8) * 2;
;     bf16x8 b0 = *reinterpret_cast<const bf16x8*>((const char*)Ks + KSWZ(r32, cb));
;     bf16x8 b1 = *reinterpret_cast<const bf16x8*>((const char*)Ks + KSWZ(32 + r32, cb));
;     p0 = __builtin_amdgcn_mfma_f32_32x32x16_bf16(b0, qr[d0], p0, 0, 0, 0);
;     p1 = __builtin_amdgcn_mfma_f32_32x32x16_bf16(b1, qr[d0], p1, 0, 0, 0); }
; }
; __device__ __forceinline__ int v_st(int k, int c) { const int kk = (k & ~0xC) | ((k & 4) << 1) | ((k & 8) >> 1); return ((kk >> 3) * 4 + (c >> 5)) * 512 + ((kk & 7) * 32 + (c & 31)) * 2; }
; __device__ __forceinline__ int v_rd_base(int lane) { return ((lane & 3) << 3) | (((lane >> 2) & 3) << 6) | (((lane >> 4) & 1) << 5) | (((lane >> 5) & 1) << 8); }
; template <int OFF> __device__ __forceinline__ s16x4 tr_read(int vb) {
;   s16x4 r; asm volatile("ds_read_b64_tr_b16 %0, %1 offset:%2" : "=&v"(r) : "v"(vb), "i"(OFF) : "memory"); return r;
; }
; template <int D0> __device__ __forceinline__ void pv_one(f32x16& od, int vb, bf16x8 pa0, bf16x8 pa1, bf16x8 pa2, bf16x8 pa3) {
;   const s16x4 l0 = tr_read<v_rd_off(D0, 0, 0)>(vb), h0 = tr_read<v_rd_off(D0, 0, 1)>(vb), l1 = tr_read<v_rd_off(D0, 1, 0)>(vb), h1 = tr_read<v_rd_off(D0, 1, 1)>(vb);
;   const s16x4 l2 = tr_read<v_rd_off(D0, 2, 0)>(vb), h2 = tr_read<v_rd_off(D0, 2, 1)>(vb), l3 = tr_read<v_rd_off(D0, 3, 0)>(vb), h3 = tr_read<v_rd_off(D0, 3, 1)>(vb);
;   asm volatile("s_waitcnt lgkmcnt(0)" ::: "memory"); SBAR();
;     ...
;   od = __builtin_amdgcn_mfma_f32_32x32x16_bf16(pa0, PK(l0, h0), od, 0, 0, 0);
;   od = __builtin_amdgcn_mfma_f32_32x32x16_bf16(pa1, PK(l1, h1), od, 0, 0, 0);
;   od = __builtin_amdgcn_mfma_f32_32x32x16_bf16(pa2, PK(l2, h2), od, 0, 0, 0);
;   od = __builtin_amdgcn_mfma_f32_32x32x16_bf16(pa3, PK(l3, h3), od, 0, 0, 0);
;     ...
; }
; __device__ __forceinline__ void pv_d0(f32x16* o, int vb, bf16x8 pa0, bf16x8 pa1, bf16x8 pa2, bf16x8 pa3) {
;   pv_one<0>(o[0], vb, pa0, pa1, pa2, pa3); pv_one<1>(o[1], vb, pa0, pa1, pa2, pa3); pv_one<2>(o[2], vb, pa0, pa1, pa2, pa3); pv_one<3>(o[3], vb, pa0, pa1, pa2, pa3);
.Lda_skipk_2:
	s_barrier
	s_setprio 3
	s_waitcnt vmcnt(4)
	ds_write_b128 v197, v[186:189] offset:16384
	ds_write_b128 v197, v[220:223] offset:24576
	ds_write_b128 v185, v[246:249] offset:16384
	ds_write_b128 v185, v[200:203] offset:24576
	s_waitcnt lgkmcnt(10)
	v_mfma_f32_32x32x16_bf16 v[80:95], v[150:153], v[130:133], 0
	v_mfma_f32_32x32x16_bf16 v[64:79], v[154:157], v[130:133], 0
	global_load_dwordx4 v[186:189], v184, s[16:17]
	global_load_dwordx4 v[220:223], v184, s[2:3]
	global_load_dwordx4 v[246:249], v184, s[14:15]
	global_load_dwordx4 v[200:203], v184, s[10:11]
	s_add_u32 s16, s16, 0x60000
	s_addc_u32 s17, s17, 0
	s_add_u32 s2, s2, 0x60000
	s_addc_u32 s3, s3, 0
	s_add_u32 s14, s14, 0x60000
	s_addc_u32 s15, s15, 0
	s_add_u32 s10, s10, 0x60000
	s_addc_u32 s11, s11, 0
	ds_read_b128 v[150:153], v208 offset:49152
	ds_read_b128 v[154:157], v208 offset:57344
	s_waitcnt lgkmcnt(10)
	v_mfma_f32_32x32x16_bf16 v[80:95], v[158:161], v[126:129], v[80:95]
	v_mfma_f32_32x32x16_bf16 v[64:79], v[162:165], v[126:129], v[64:79]
	ds_read_b128 v[158:161], v209 offset:49152
	ds_read_b128 v[162:165], v209 offset:57344
	s_waitcnt lgkmcnt(10)
	v_mfma_f32_32x32x16_bf16 v[80:95], v[228:231], v[122:125], v[80:95]
	v_mfma_f32_32x32x16_bf16 v[64:79], v[232:235], v[122:125], v[64:79]
	ds_read_b128 v[228:231], v210 offset:49152
	ds_read_b128 v[232:235], v210 offset:57344
	s_waitcnt lgkmcnt(10)
	v_mfma_f32_32x32x16_bf16 v[80:95], v[236:239], v[118:121], v[80:95]
	v_mfma_f32_32x32x16_bf16 v[64:79], v[240:243], v[118:121], v[64:79]
	ds_read_b128 v[236:239], v211 offset:49152
	ds_read_b128 v[240:243], v211 offset:57344
	s_waitcnt lgkmcnt(6)
	v_mfma_f32_32x32x16_bf16 v[80:95], v[150:153], v[114:117], v[80:95]
	v_mfma_f32_32x32x16_bf16 v[64:79], v[154:157], v[114:117], v[64:79]
	ds_read_b64_tr_b16 v[150:151], v196 offset:32768
	ds_read_b64_tr_b16 v[152:153], v196 offset:34816
	ds_read_b64_tr_b16 v[154:155], v196 offset:36864
	ds_read_b64_tr_b16 v[156:157], v196 offset:38912
	s_waitcnt lgkmcnt(8)
	v_mfma_f32_32x32x16_bf16 v[80:95], v[158:161], v[110:113], v[80:95]
	v_mfma_f32_32x32x16_bf16 v[64:79], v[162:165], v[110:113], v[64:79]
	ds_read_b64_tr_b16 v[158:159], v196 offset:40960
	ds_read_b64_tr_b16 v[160:161], v196 offset:43008
	ds_read_b64_tr_b16 v[162:163], v196 offset:45056
	ds_read_b64_tr_b16 v[164:165], v196 offset:47104
	s_waitcnt lgkmcnt(10)
	v_mfma_f32_32x32x16_bf16 v[80:95], v[228:231], v[106:109], v[80:95]
	v_mfma_f32_32x32x16_bf16 v[64:79], v[232:235], v[106:109], v[64:79]
	ds_read_b64_tr_b16 v[228:229], v196 offset:33280
	ds_read_b64_tr_b16 v[230:231], v196 offset:35328
	ds_read_b64_tr_b16 v[232:233], v196 offset:37376
	ds_read_b64_tr_b16 v[234:235], v196 offset:39424
	s_waitcnt lgkmcnt(12)
	v_mfma_f32_32x32x16_bf16 v[80:95], v[236:239], v[102:105], v[80:95]
	v_mfma_f32_32x32x16_bf16 v[64:79], v[240:243], v[102:105], v[64:79]
	ds_read_b64_tr_b16 v[236:237], v196 offset:41472
	ds_read_b64_tr_b16 v[238:239], v196 offset:43520
	s_waitcnt lgkmcnt(12)
	v_mfma_f32_32x32x16_bf16 v[0:15], v[166:169], v[150:153], v[0:15]
	ds_read_b64_tr_b16 v[240:241], v196 offset:45568
	ds_read_b64_tr_b16 v[242:243], v196 offset:47616
	s_waitcnt lgkmcnt(12)
	v_mfma_f32_32x32x16_bf16 v[0:15], v[170:173], v[154:157], v[0:15]
	ds_read_b64_tr_b16 v[150:151], v196 offset:33792
	ds_read_b64_tr_b16 v[152:153], v196 offset:35840
	s_waitcnt lgkmcnt(12)
	v_mfma_f32_32x32x16_bf16 v[0:15], v[176:179], v[158:161], v[0:15]
	ds_read_b64_tr_b16 v[154:155], v196 offset:37888
	ds_read_b64_tr_b16 v[156:157], v196 offset:39936
	s_waitcnt lgkmcnt(12)
	v_mfma_f32_32x32x16_bf16 v[0:15], v[180:183], v[162:165], v[0:15]
	ds_read_b64_tr_b16 v[158:159], v196 offset:41984
	ds_read_b64_tr_b16 v[160:161], v196 offset:44032
	s_waitcnt lgkmcnt(12)
	v_mfma_f32_32x32x16_bf16 v[48:63], v[166:169], v[228:231], v[48:63]
	ds_read_b64_tr_b16 v[162:163], v196 offset:46080
	ds_read_b64_tr_b16 v[164:165], v196 offset:48128
	s_waitcnt lgkmcnt(12)
	v_mfma_f32_32x32x16_bf16 v[48:63], v[170:173], v[232:235], v[48:63]
	ds_read_b64_tr_b16 v[228:229], v196 offset:34304
	ds_read_b64_tr_b16 v[230:231], v196 offset:36352
	s_waitcnt lgkmcnt(12)
	v_mfma_f32_32x32x16_bf16 v[48:63], v[176:179], v[236:239], v[48:63]
	ds_read_b64_tr_b16 v[232:233], v196 offset:38400
	ds_read_b64_tr_b16 v[234:235], v196 offset:40448
	s_waitcnt lgkmcnt(12)
	v_mfma_f32_32x32x16_bf16 v[48:63], v[180:183], v[240:243], v[48:63]
	ds_read_b64_tr_b16 v[236:237], v196 offset:42496
	ds_read_b64_tr_b16 v[238:239], v196 offset:44544
	s_waitcnt lgkmcnt(12)
	v_mfma_f32_32x32x16_bf16 v[32:47], v[166:169], v[150:153], v[32:47]
	ds_read_b64_tr_b16 v[240:241], v196 offset:46592
	ds_read_b64_tr_b16 v[242:243], v196 offset:48640
	s_waitcnt lgkmcnt(12)
	v_mfma_f32_32x32x16_bf16 v[32:47], v[170:173], v[154:157], v[32:47]
	s_waitcnt lgkmcnt(10)
	v_mfma_f32_32x32x16_bf16 v[32:47], v[176:179], v[158:161], v[32:47]
	s_waitcnt lgkmcnt(8)
	v_mfma_f32_32x32x16_bf16 v[32:47], v[180:183], v[162:165], v[32:47]
	s_waitcnt lgkmcnt(6)
	v_mfma_f32_32x32x16_bf16 v[16:31], v[166:169], v[228:231], v[16:31]
	s_waitcnt lgkmcnt(4)
	v_mfma_f32_32x32x16_bf16 v[16:31], v[170:173], v[232:235], v[16:31]
	s_waitcnt lgkmcnt(2)
	v_mfma_f32_32x32x16_bf16 v[16:31], v[176:179], v[236:239], v[16:31]
	s_waitcnt lgkmcnt(0)
	v_mfma_f32_32x32x16_bf16 v[16:31], v[180:183], v[240:243], v[16:31]
	s_setprio 0
	s_barrier
; __device__ __forceinline__ void partialSM(f32x16& p0, f32x16& p1, float& m_reg, float& mn, float& alpha) {
;   constexpr float C = SCALE * 1.4426950408889634f;
;   float pmax = p0[0];
; #pragma unroll
;   for (int r = 1; r < 16; ++r) pmax = fmaxf(pmax, p0[r]);
; #pragma unroll
;   for (int r = 0; r < 16; ++r) pmax = fmaxf(pmax, p1[r]);
;   { auto rr = __builtin_amdgcn_permlane32_swap(__float_as_uint(pmax), __float_as_uint(pmax), false, false);
;     pmax = fmaxf(__uint_as_float(rr[0]), __uint_as_float(rr[1])); }
;   if (__builtin_expect(__all(pmax - m_reg <= THR / SCALE), 1)) { mn = m_reg; alpha = 1.f; }
;   else { mn = fmaxf(m_reg, pmax); alpha = __builtin_amdgcn_exp2f((m_reg - mn) * C); m_reg = mn; }
;   float mnC = -mn * C;
; #pragma unroll
;   for (int r = 0; r < 16; ++r) p0[r] = fmaf(p0[r], C, mnC);
; #pragma unroll
;   for (int r = 0; r < 16; ++r) p1[r] = fmaf(p1[r], C, mnC);
; #pragma unroll
;   for (int r = 0; r < 16; ++r) p0[r] = __builtin_amdgcn_exp2f(p0[r]);
; }
	v_max3_f32 v190, v80, v81, v82
	v_max3_f32 v191, v64, v65, v66
	v_max3_f32 v190, v190, v83, v84
	v_max3_f32 v191, v191, v67, v68
	v_max3_f32 v190, v190, v85, v86
	v_max3_f32 v191, v191, v69, v70
	v_max3_f32 v190, v190, v87, v88
	v_max3_f32 v191, v191, v71, v72
	v_max3_f32 v190, v190, v89, v90
	v_max3_f32 v191, v191, v73, v74
	v_max3_f32 v190, v190, v91, v92
	v_max3_f32 v191, v191, v75, v76
	v_max3_f32 v190, v190, v93, v94
	v_max3_f32 v191, v191, v77, v78
	v_max3_f32 v190, v190, v95, v79
	v_max_f32_e32 v190, v190, v191
	v_mov_b32_e32 v191, v190
	s_nop 1
	v_permlane32_swap_b32_e32 v190, v191
	s_nop 0
	v_max_f32_e32 v212, v190, v191
	v_sub_f32_e32 v190, v212, v174
	v_cmp_ge_f32_e32 vcc, s86, v190
	v_max_f32_e32 v191, v174, v212
	v_sub_f32_e32 v215, v174, v191
	v_mul_f32_e32 v215, s92, v215
	s_nop 1
	s_cmp_eq_u64 vcc, exec
	s_cselect_b64 s[42:43], -1, 0
	v_exp_f32_e32 v213, v215
	s_nop 0
	v_cndmask_b32_e64 v174, v191, v174, s[42:43]
	v_cndmask_b32_e64 v213, v213, 1.0, s[42:43]
	v_mul_f32_e32 v214, 0xbe0293ee, v174
	s_nop 0
	v_cmp_gt_f32_e32 vcc, 1.0, v213
	v_fma_f32 v80, v80, s92, v214
	v_fma_f32 v81, v81, s92, v214
	v_fma_f32 v82, v82, s92, v214
	v_fma_f32 v83, v83, s92, v214
	v_fma_f32 v84, v84, s92, v214
	v_fma_f32 v85, v85, s92, v214
	v_fma_f32 v86, v86, s92, v214
	v_fma_f32 v87, v87, s92, v214
	v_fma_f32 v88, v88, s92, v214
	v_fma_f32 v89, v89, s92, v214
	v_fma_f32 v90, v90, s92, v214
	v_fma_f32 v91, v91, s92, v214
	v_fma_f32 v92, v92, s92, v214
	v_fma_f32 v93, v93, s92, v214
	v_fma_f32 v94, v94, s92, v214
	v_fma_f32 v95, v95, s92, v214
	v_fma_f32 v64, v64, s92, v214
	v_fma_f32 v65, v65, s92, v214
	v_fma_f32 v66, v66, s92, v214
	v_fma_f32 v67, v67, s92, v214
	v_fma_f32 v68, v68, s92, v214
	v_fma_f32 v69, v69, s92, v214
	v_fma_f32 v70, v70, s92, v214
	v_fma_f32 v71, v71, s92, v214
	v_fma_f32 v72, v72, s92, v214
	v_fma_f32 v73, v73, s92, v214
	v_fma_f32 v74, v74, s92, v214
	v_fma_f32 v75, v75, s92, v214
	v_fma_f32 v76, v76, s92, v214
	v_fma_f32 v77, v77, s92, v214
	v_fma_f32 v78, v78, s92, v214
	v_fma_f32 v79, v79, s92, v214
	s_cbranch_vccz .Lda_noresc_3
	s_and_saveexec_b64 s[12:13], s[40:41]
	ds_write_b32 v199, v213 offset:128
	s_or_b64 exec, exec, s[12:13]
	s_waitcnt lgkmcnt(0)
	v_add_u32_e32 v215, v99, v96
	ds_read_b128 v[228:231], v215 offset:128
	ds_read_b128 v[232:235], v215 offset:160
	ds_read_b128 v[236:239], v215 offset:192
	ds_read_b128 v[240:243], v215 offset:224
	s_waitcnt lgkmcnt(0)
	v_pk_mul_f32 v[0:1], v[0:1], v[228:229]
	v_pk_mul_f32 v[2:3], v[2:3], v[230:231]
	v_pk_mul_f32 v[4:5], v[4:5], v[232:233]
	v_pk_mul_f32 v[6:7], v[6:7], v[234:235]
	v_pk_mul_f32 v[8:9], v[8:9], v[236:237]
	v_pk_mul_f32 v[10:11], v[10:11], v[238:239]
	v_pk_mul_f32 v[12:13], v[12:13], v[240:241]
	v_pk_mul_f32 v[14:15], v[14:15], v[242:243]
	v_pk_mul_f32 v[48:49], v[48:49], v[228:229]
	v_pk_mul_f32 v[50:51], v[50:51], v[230:231]
	v_pk_mul_f32 v[52:53], v[52:53], v[232:233]
	v_pk_mul_f32 v[54:55], v[54:55], v[234:235]
	v_pk_mul_f32 v[56:57], v[56:57], v[236:237]
	v_pk_mul_f32 v[58:59], v[58:59], v[238:239]
	v_pk_mul_f32 v[60:61], v[60:61], v[240:241]
	v_pk_mul_f32 v[62:63], v[62:63], v[242:243]
	v_pk_mul_f32 v[32:33], v[32:33], v[228:229]
	v_pk_mul_f32 v[34:35], v[34:35], v[230:231]
	v_pk_mul_f32 v[36:37], v[36:37], v[232:233]
	v_pk_mul_f32 v[38:39], v[38:39], v[234:235]
	v_pk_mul_f32 v[40:41], v[40:41], v[236:237]
	v_pk_mul_f32 v[42:43], v[42:43], v[238:239]
	v_pk_mul_f32 v[44:45], v[44:45], v[240:241]
	v_pk_mul_f32 v[46:47], v[46:47], v[242:243]
	v_pk_mul_f32 v[16:17], v[16:17], v[228:229]
	v_pk_mul_f32 v[18:19], v[18:19], v[230:231]
	v_pk_mul_f32 v[20:21], v[20:21], v[232:233]
	v_pk_mul_f32 v[22:23], v[22:23], v[234:235]
	v_pk_mul_f32 v[24:25], v[24:25], v[236:237]
	v_pk_mul_f32 v[26:27], v[26:27], v[238:239]
	v_pk_mul_f32 v[28:29], v[28:29], v[240:241]
	v_pk_mul_f32 v[30:31], v[30:31], v[242:243]
